# phase 0: the S5 parameter item's 4-trip loop is unrolled with all 40 loads issued up front (its trips no longer wait for each other's scattered stores)
# speedup vs baseline: 1.0091x; 1.0091x over previous
; DEVINL u16 f2bf(float f) { return (u16)((__float_as_uint(f) + 0x8000u) >> 16); }
; DEVINL void s5_param(const Params& p, int idx) {
;     ...
;   for (int j = 0; j < 16; ++j) {
;     float br = p.b_re[(size_t)idx * 16 + j], bi = p.b_im[(size_t)idx * 16 + j];
;     bbt[((size_t)g * 128 + 2 * n) * 16 + j] = f2bf(fr * br - fi * bi);
;     bbt[((size_t)g * 128 + 2 * n + 1) * 16 + j] = f2bf(fr * bi + fi * br);
;     ct[((size_t)g * 16 + j) * 128 + 2 * n] = f2bf(p.c_re[((size_t)g * 16 + j) * 64 + n]);
;     ct[((size_t)g * 16 + j) * 128 + 2 * n + 1] = f2bf(-p.c_im[((size_t)g * 16 + j) * 64 + n]);
;   }
.LBB0_1474:
	v_lshl_add_u64 v[206:207], v[8:9], 0, s[14:15]
	v_lshlrev_b64 v[206:207], 2, v[206:207]
	v_lshl_add_u64 v[208:209], s[80:81], 0, v[206:207]
	global_load_dwordx4 v[210:213], v[208:209], off offset:0
	global_load_dwordx4 v[132:135], v[208:209], off offset:16
	global_load_dwordx4 v[148:151], v[208:209], off offset:32
	global_load_dwordx4 v[164:167], v[208:209], off offset:48
	v_lshl_add_u64 v[208:209], s[78:79], 0, v[206:207]
	global_load_dwordx4 v[214:217], v[208:209], off offset:0
	global_load_dwordx4 v[136:139], v[208:209], off offset:16
	global_load_dwordx4 v[152:155], v[208:209], off offset:32
	global_load_dwordx4 v[168:171], v[208:209], off offset:48
	v_lshl_add_u64 v[206:207], v[14:15], 0, s[14:15]
	v_lshlrev_b64 v[206:207], 8, v[206:207]
	v_lshlrev_b32_e32 v205, 2, v4
	v_or_b32_e32 v206, v206, v205
	v_lshl_add_u64 v[208:209], s[82:83], 0, v[206:207]
	global_load_dword v218, v[208:209], off
	global_load_dword v219, v[208:209], off offset:256
	global_load_dword v220, v[208:209], off offset:512
	global_load_dword v221, v[208:209], off offset:768
	global_load_dword v140, v[208:209], off offset:1024
	global_load_dword v141, v[208:209], off offset:1280
	global_load_dword v142, v[208:209], off offset:1536
	global_load_dword v143, v[208:209], off offset:1792
	global_load_dword v156, v[208:209], off offset:2048
	global_load_dword v157, v[208:209], off offset:2304
	global_load_dword v158, v[208:209], off offset:2560
	global_load_dword v159, v[208:209], off offset:2816
	global_load_dword v172, v[208:209], off offset:3072
	global_load_dword v173, v[208:209], off offset:3328
	global_load_dword v174, v[208:209], off offset:3584
	global_load_dword v175, v[208:209], off offset:3840
	v_lshl_add_u64 v[208:209], s[4:5], 0, v[206:207]
	global_load_dword v222, v[208:209], off
	global_load_dword v223, v[208:209], off offset:256
	global_load_dword v224, v[208:209], off offset:512
	global_load_dword v225, v[208:209], off offset:768
	global_load_dword v144, v[208:209], off offset:1024
	global_load_dword v145, v[208:209], off offset:1280
	global_load_dword v146, v[208:209], off offset:1536
	global_load_dword v147, v[208:209], off offset:1792
	global_load_dword v160, v[208:209], off offset:2048
	global_load_dword v161, v[208:209], off offset:2304
	global_load_dword v162, v[208:209], off offset:2560
	global_load_dword v163, v[208:209], off offset:2816
	global_load_dword v176, v[208:209], off offset:3072
	global_load_dword v177, v[208:209], off offset:3328
	global_load_dword v178, v[208:209], off offset:3584
	global_load_dword v179, v[208:209], off offset:3840
	s_waitcnt vmcnt(0)
	v_lshl_add_u64 v[22:23], v[8:9], 0, s[14:15]
	v_lshlrev_b64 v[22:23], 2, v[22:23]
	v_lshl_add_u64 v[24:25], s[78:79], 0, v[22:23]
	v_lshl_add_u64 v[22:23], s[80:81], 0, v[22:23]
	v_mov_b32_e32 v22, v210
	v_mov_b32_e32 v23, v211
	s_mov_b32 s37, s15
	v_mov_b32_e32 v24, v214
	v_mov_b32_e32 v25, v215
	s_add_i32 s38, s14, 2
	s_mov_b32 s39, s15
	s_add_i32 s34, s36, 2
	s_mov_b32 s35, s15
	s_add_i32 s0, s0, -4
	v_pk_mul_f32 v[26:27], v[16:17], v[22:23]
	v_pk_mul_f32 v[22:23], v[18:19], v[22:23]
	v_pk_fma_f32 v[26:27], v[18:19], v[24:25], v[26:27] neg_lo:[0,0,1] neg_hi:[0,0,1]
	v_pk_fma_f32 v[22:23], v[16:17], v[24:25], v[22:23]
	v_add_u32_e32 v3, 0x8000, v26
	v_add_u32_e32 v5, 0x8000, v27
	v_perm_b32 v3, v5, v3, s25
	v_lshl_add_u64 v[26:27], s[14:15], 1, v[10:11]
	global_store_dword v[26:27], v3, off
	v_add_u32_e32 v3, 0x8000, v22
	v_add_u32_e32 v5, 0x8000, v23
	v_perm_b32 v3, v5, v3, s25
	v_lshl_add_u64 v[24:25], v[14:15], 0, s[14:15]
	global_store_dword v[26:27], v3, off offset:32
	v_lshl_add_u64 v[22:23], v[20:21], 0, s[36:37]
	v_lshlrev_b64 v[24:25], 8, v[24:25]
	v_lshlrev_b32_e32 v3, 2, v4
	v_or_b32_e32 v26, v24, v3
	v_mov_b32_e32 v27, v25
	v_lshlrev_b64 v[22:23], 8, v[22:23]
	v_lshlrev_b32_e32 v5, 2, v6
	v_lshl_add_u64 v[28:29], s[82:83], 0, v[26:27]
	v_or_b32_e32 v30, v22, v5
	v_mov_b32_e32 v31, v23
	v_lshl_add_u64 v[32:33], s[82:83], 0, v[30:31]
	v_mov_b32_e32 v7, v218
	s_nop 0
	v_mov_b32_e32 v28, v219
	v_lshl_add_u64 v[24:25], v[12:13], 0, v[24:25]
	v_lshl_add_u64 v[22:23], v[12:13], 0, v[22:23]
	v_lshl_add_u64 v[26:27], s[4:5], 0, v[26:27]
	s_add_i32 s14, s14, 4
	s_add_i32 s36, s36, 4
	s_cmp_lg_u32 s0, 0
	v_add_u32_e32 v7, 0x8000, v7
	v_add_u32_e32 v28, 0x8000, v28
	global_store_short_d16_hi v[24:25], v7, off
	global_store_short_d16_hi v[22:23], v28, off
	v_lshl_add_u64 v[28:29], s[4:5], 0, v[30:31]
	v_mov_b32_e32 v26, v222
	s_nop 0
	v_mov_b32_e32 v27, v223
	v_pk_add_f32 v[26:27], v[26:27], 0 neg_lo:[1,1] neg_hi:[1,1]
	s_nop 0
	v_add_u32_e32 v26, 0x8000, v26
	v_add_u32_e32 v7, 0x8000, v27
	global_store_short_d16_hi v[24:25], v26, off offset:2
	global_store_short_d16_hi v[22:23], v7, off offset:2
	v_lshl_add_u64 v[22:23], v[8:9], 0, s[38:39]
	v_lshlrev_b64 v[22:23], 2, v[22:23]
	v_lshl_add_u64 v[24:25], s[78:79], 0, v[22:23]
	v_lshl_add_u64 v[22:23], s[80:81], 0, v[22:23]
	v_mov_b32_e32 v22, v212
	v_mov_b32_e32 v23, v213
	v_pk_mul_f32 v[26:27], v[16:17], v[22:23]
	v_mov_b32_e32 v24, v216
	v_mov_b32_e32 v25, v217
	v_pk_mul_f32 v[22:23], v[18:19], v[22:23]
	v_pk_fma_f32 v[26:27], v[18:19], v[24:25], v[26:27] neg_lo:[0,0,1] neg_hi:[0,0,1]
	s_nop 0
	v_add_u32_e32 v7, 0x8000, v26
	v_add_u32_e32 v26, 0x8000, v27
	v_perm_b32 v7, v26, v7, s25
	v_lshl_add_u64 v[26:27], s[38:39], 1, v[10:11]
	v_pk_fma_f32 v[22:23], v[16:17], v[24:25], v[22:23]
	global_store_dword v[26:27], v7, off
	v_add_u32_e32 v7, 0x8000, v22
	v_add_u32_e32 v22, 0x8000, v23
	v_lshl_add_u64 v[24:25], v[14:15], 0, s[38:39]
	v_perm_b32 v7, v22, v7, s25
	v_lshl_add_u64 v[22:23], v[20:21], 0, s[34:35]
; DEVINL u16 f2bf(float f) { return (u16)((__float_as_uint(f) + 0x8000u) >> 16); }
; DEVINL void s5_param(const Params& p, int idx) {
;     ...
;   for (int j = 0; j < 16; ++j) {
;     float br = p.b_re[(size_t)idx * 16 + j], bi = p.b_im[(size_t)idx * 16 + j];
;     bbt[((size_t)g * 128 + 2 * n) * 16 + j] = f2bf(fr * br - fi * bi);
;     bbt[((size_t)g * 128 + 2 * n + 1) * 16 + j] = f2bf(fr * bi + fi * br);
;     ct[((size_t)g * 16 + j) * 128 + 2 * n] = f2bf(p.c_re[((size_t)g * 16 + j) * 64 + n]);
;     ct[((size_t)g * 16 + j) * 128 + 2 * n + 1] = f2bf(-p.c_im[((size_t)g * 16 + j) * 64 + n]);
;   }
	v_lshlrev_b64 v[24:25], 8, v[24:25]
	global_store_dword v[26:27], v7, off offset:32
	v_or_b32_e32 v26, v24, v3
	v_mov_b32_e32 v27, v25
	v_lshlrev_b64 v[22:23], 8, v[22:23]
	v_lshl_add_u64 v[28:29], s[82:83], 0, v[26:27]
	v_or_b32_e32 v30, v22, v5
	v_mov_b32_e32 v31, v23
	v_lshl_add_u64 v[32:33], s[82:83], 0, v[30:31]
	v_mov_b32_e32 v3, v220
	v_mov_b32_e32 v5, v221
	v_lshl_add_u64 v[24:25], v[12:13], 0, v[24:25]
	v_lshl_add_u64 v[22:23], v[12:13], 0, v[22:23]
	v_lshl_add_u64 v[26:27], s[4:5], 0, v[26:27]
	v_lshl_add_u64 v[28:29], s[4:5], 0, v[30:31]
	v_add_u32_e32 v3, 0x8000, v3
	v_add_u32_e32 v5, 0x8000, v5
	global_store_short_d16_hi v[24:25], v3, off
	global_store_short_d16_hi v[22:23], v5, off
	v_mov_b32_e32 v26, v224
	s_nop 0
	v_mov_b32_e32 v27, v225
	v_pk_add_f32 v[26:27], v[26:27], 0 neg_lo:[1,1] neg_hi:[1,1]
	s_nop 0
	v_add_u32_e32 v5, 0x8000, v26
	v_add_u32_e32 v3, 0x8000, v27
	global_store_short_d16_hi v[24:25], v5, off offset:2
	global_store_short_d16_hi v[22:23], v3, off offset:2
	v_lshl_add_u64 v[22:23], v[8:9], 0, s[14:15]
	v_lshlrev_b64 v[22:23], 2, v[22:23]
	v_lshl_add_u64 v[24:25], s[78:79], 0, v[22:23]
	v_lshl_add_u64 v[22:23], s[80:81], 0, v[22:23]
	v_mov_b32_e32 v22, v132
	v_mov_b32_e32 v23, v133
	s_mov_b32 s37, s15
	v_mov_b32_e32 v24, v136
	v_mov_b32_e32 v25, v137
	s_add_i32 s38, s14, 2
	s_mov_b32 s39, s15
	s_add_i32 s34, s36, 2
	s_mov_b32 s35, s15
	s_add_i32 s0, s0, -4
	v_pk_mul_f32 v[26:27], v[16:17], v[22:23]
	v_pk_mul_f32 v[22:23], v[18:19], v[22:23]
	v_pk_fma_f32 v[26:27], v[18:19], v[24:25], v[26:27] neg_lo:[0,0,1] neg_hi:[0,0,1]
	v_pk_fma_f32 v[22:23], v[16:17], v[24:25], v[22:23]
	v_add_u32_e32 v3, 0x8000, v26
	v_add_u32_e32 v5, 0x8000, v27
	v_perm_b32 v3, v5, v3, s25
	v_lshl_add_u64 v[26:27], s[14:15], 1, v[10:11]
	global_store_dword v[26:27], v3, off
	v_add_u32_e32 v3, 0x8000, v22
	v_add_u32_e32 v5, 0x8000, v23
	v_perm_b32 v3, v5, v3, s25
	v_lshl_add_u64 v[24:25], v[14:15], 0, s[14:15]
	global_store_dword v[26:27], v3, off offset:32
	v_lshl_add_u64 v[22:23], v[20:21], 0, s[36:37]
	v_lshlrev_b64 v[24:25], 8, v[24:25]
	v_lshlrev_b32_e32 v3, 2, v4
	v_or_b32_e32 v26, v24, v3
	v_mov_b32_e32 v27, v25
	v_lshlrev_b64 v[22:23], 8, v[22:23]
	v_lshlrev_b32_e32 v5, 2, v6
	v_lshl_add_u64 v[28:29], s[82:83], 0, v[26:27]
	v_or_b32_e32 v30, v22, v5
	v_mov_b32_e32 v31, v23
	v_lshl_add_u64 v[32:33], s[82:83], 0, v[30:31]
	v_mov_b32_e32 v7, v140
	s_nop 0
	v_mov_b32_e32 v28, v141
	v_lshl_add_u64 v[24:25], v[12:13], 0, v[24:25]
	v_lshl_add_u64 v[22:23], v[12:13], 0, v[22:23]
	v_lshl_add_u64 v[26:27], s[4:5], 0, v[26:27]
	s_add_i32 s14, s14, 4
	s_add_i32 s36, s36, 4
	s_cmp_lg_u32 s0, 0
	v_add_u32_e32 v7, 0x8000, v7
	v_add_u32_e32 v28, 0x8000, v28
	global_store_short_d16_hi v[24:25], v7, off
	global_store_short_d16_hi v[22:23], v28, off
	v_lshl_add_u64 v[28:29], s[4:5], 0, v[30:31]
	v_mov_b32_e32 v26, v144
	s_nop 0
	v_mov_b32_e32 v27, v145
	v_pk_add_f32 v[26:27], v[26:27], 0 neg_lo:[1,1] neg_hi:[1,1]
	s_nop 0
	v_add_u32_e32 v26, 0x8000, v26
	v_add_u32_e32 v7, 0x8000, v27
	global_store_short_d16_hi v[24:25], v26, off offset:2
	global_store_short_d16_hi v[22:23], v7, off offset:2
	v_lshl_add_u64 v[22:23], v[8:9], 0, s[38:39]
	v_lshlrev_b64 v[22:23], 2, v[22:23]
	v_lshl_add_u64 v[24:25], s[78:79], 0, v[22:23]
	v_lshl_add_u64 v[22:23], s[80:81], 0, v[22:23]
	v_mov_b32_e32 v22, v134
	v_mov_b32_e32 v23, v135
	v_pk_mul_f32 v[26:27], v[16:17], v[22:23]
	v_mov_b32_e32 v24, v138
	v_mov_b32_e32 v25, v139
	v_pk_mul_f32 v[22:23], v[18:19], v[22:23]
	v_pk_fma_f32 v[26:27], v[18:19], v[24:25], v[26:27] neg_lo:[0,0,1] neg_hi:[0,0,1]
	s_nop 0
	v_add_u32_e32 v7, 0x8000, v26
	v_add_u32_e32 v26, 0x8000, v27
	v_perm_b32 v7, v26, v7, s25
	v_lshl_add_u64 v[26:27], s[38:39], 1, v[10:11]
	v_pk_fma_f32 v[22:23], v[16:17], v[24:25], v[22:23]
	global_store_dword v[26:27], v7, off
	v_add_u32_e32 v7, 0x8000, v22
	v_add_u32_e32 v22, 0x8000, v23
	v_lshl_add_u64 v[24:25], v[14:15], 0, s[38:39]
	v_perm_b32 v7, v22, v7, s25
	v_lshl_add_u64 v[22:23], v[20:21], 0, s[34:35]
	v_lshlrev_b64 v[24:25], 8, v[24:25]
	global_store_dword v[26:27], v7, off offset:32
	v_or_b32_e32 v26, v24, v3
	v_mov_b32_e32 v27, v25
	v_lshlrev_b64 v[22:23], 8, v[22:23]
	v_lshl_add_u64 v[28:29], s[82:83], 0, v[26:27]
	v_or_b32_e32 v30, v22, v5
	v_mov_b32_e32 v31, v23
	v_lshl_add_u64 v[32:33], s[82:83], 0, v[30:31]
	v_mov_b32_e32 v3, v142
	v_mov_b32_e32 v5, v143
	v_lshl_add_u64 v[24:25], v[12:13], 0, v[24:25]
	v_lshl_add_u64 v[22:23], v[12:13], 0, v[22:23]
	v_lshl_add_u64 v[26:27], s[4:5], 0, v[26:27]
	v_lshl_add_u64 v[28:29], s[4:5], 0, v[30:31]
	v_add_u32_e32 v3, 0x8000, v3
	v_add_u32_e32 v5, 0x8000, v5
	global_store_short_d16_hi v[24:25], v3, off
	global_store_short_d16_hi v[22:23], v5, off
	v_mov_b32_e32 v26, v146
	s_nop 0
	v_mov_b32_e32 v27, v147
	v_pk_add_f32 v[26:27], v[26:27], 0 neg_lo:[1,1] neg_hi:[1,1]
	s_nop 0
	v_add_u32_e32 v5, 0x8000, v26
	v_add_u32_e32 v3, 0x8000, v27
	global_store_short_d16_hi v[24:25], v5, off offset:2
	global_store_short_d16_hi v[22:23], v3, off offset:2
	v_lshl_add_u64 v[22:23], v[8:9], 0, s[14:15]
	v_lshlrev_b64 v[22:23], 2, v[22:23]
	v_lshl_add_u64 v[24:25], s[78:79], 0, v[22:23]
	v_lshl_add_u64 v[22:23], s[80:81], 0, v[22:23]
	v_mov_b32_e32 v22, v148
	v_mov_b32_e32 v23, v149
	s_mov_b32 s37, s15
	v_mov_b32_e32 v24, v152
	v_mov_b32_e32 v25, v153
	s_add_i32 s38, s14, 2
	s_mov_b32 s39, s15
	s_add_i32 s34, s36, 2
	s_mov_b32 s35, s15
	s_add_i32 s0, s0, -4
	v_pk_mul_f32 v[26:27], v[16:17], v[22:23]
	v_pk_mul_f32 v[22:23], v[18:19], v[22:23]
	v_pk_fma_f32 v[26:27], v[18:19], v[24:25], v[26:27] neg_lo:[0,0,1] neg_hi:[0,0,1]
	v_pk_fma_f32 v[22:23], v[16:17], v[24:25], v[22:23]
; DEVINL u16 f2bf(float f) { return (u16)((__float_as_uint(f) + 0x8000u) >> 16); }
; DEVINL void s5_param(const Params& p, int idx) {
;     ...
;   for (int j = 0; j < 16; ++j) {
;     float br = p.b_re[(size_t)idx * 16 + j], bi = p.b_im[(size_t)idx * 16 + j];
;     bbt[((size_t)g * 128 + 2 * n) * 16 + j] = f2bf(fr * br - fi * bi);
;     bbt[((size_t)g * 128 + 2 * n + 1) * 16 + j] = f2bf(fr * bi + fi * br);
;     ct[((size_t)g * 16 + j) * 128 + 2 * n] = f2bf(p.c_re[((size_t)g * 16 + j) * 64 + n]);
;     ct[((size_t)g * 16 + j) * 128 + 2 * n + 1] = f2bf(-p.c_im[((size_t)g * 16 + j) * 64 + n]);
;   }
	v_add_u32_e32 v3, 0x8000, v26
	v_add_u32_e32 v5, 0x8000, v27
	v_perm_b32 v3, v5, v3, s25
	v_lshl_add_u64 v[26:27], s[14:15], 1, v[10:11]
	global_store_dword v[26:27], v3, off
	v_add_u32_e32 v3, 0x8000, v22
	v_add_u32_e32 v5, 0x8000, v23
	v_perm_b32 v3, v5, v3, s25
	v_lshl_add_u64 v[24:25], v[14:15], 0, s[14:15]
	global_store_dword v[26:27], v3, off offset:32
	v_lshl_add_u64 v[22:23], v[20:21], 0, s[36:37]
	v_lshlrev_b64 v[24:25], 8, v[24:25]
	v_lshlrev_b32_e32 v3, 2, v4
	v_or_b32_e32 v26, v24, v3
	v_mov_b32_e32 v27, v25
	v_lshlrev_b64 v[22:23], 8, v[22:23]
	v_lshlrev_b32_e32 v5, 2, v6
	v_lshl_add_u64 v[28:29], s[82:83], 0, v[26:27]
	v_or_b32_e32 v30, v22, v5
	v_mov_b32_e32 v31, v23
	v_lshl_add_u64 v[32:33], s[82:83], 0, v[30:31]
	v_mov_b32_e32 v7, v156
	s_nop 0
	v_mov_b32_e32 v28, v157
	v_lshl_add_u64 v[24:25], v[12:13], 0, v[24:25]
	v_lshl_add_u64 v[22:23], v[12:13], 0, v[22:23]
	v_lshl_add_u64 v[26:27], s[4:5], 0, v[26:27]
	s_add_i32 s14, s14, 4
	s_add_i32 s36, s36, 4
	s_cmp_lg_u32 s0, 0
	v_add_u32_e32 v7, 0x8000, v7
	v_add_u32_e32 v28, 0x8000, v28
	global_store_short_d16_hi v[24:25], v7, off
	global_store_short_d16_hi v[22:23], v28, off
	v_lshl_add_u64 v[28:29], s[4:5], 0, v[30:31]
	v_mov_b32_e32 v26, v160
	s_nop 0
	v_mov_b32_e32 v27, v161
	v_pk_add_f32 v[26:27], v[26:27], 0 neg_lo:[1,1] neg_hi:[1,1]
	s_nop 0
	v_add_u32_e32 v26, 0x8000, v26
	v_add_u32_e32 v7, 0x8000, v27
	global_store_short_d16_hi v[24:25], v26, off offset:2
	global_store_short_d16_hi v[22:23], v7, off offset:2
	v_lshl_add_u64 v[22:23], v[8:9], 0, s[38:39]
	v_lshlrev_b64 v[22:23], 2, v[22:23]
	v_lshl_add_u64 v[24:25], s[78:79], 0, v[22:23]
	v_lshl_add_u64 v[22:23], s[80:81], 0, v[22:23]
	v_mov_b32_e32 v22, v150
	v_mov_b32_e32 v23, v151
	v_pk_mul_f32 v[26:27], v[16:17], v[22:23]
	v_mov_b32_e32 v24, v154
	v_mov_b32_e32 v25, v155
	v_pk_mul_f32 v[22:23], v[18:19], v[22:23]
	v_pk_fma_f32 v[26:27], v[18:19], v[24:25], v[26:27] neg_lo:[0,0,1] neg_hi:[0,0,1]
	s_nop 0
	v_add_u32_e32 v7, 0x8000, v26
	v_add_u32_e32 v26, 0x8000, v27
	v_perm_b32 v7, v26, v7, s25
	v_lshl_add_u64 v[26:27], s[38:39], 1, v[10:11]
	v_pk_fma_f32 v[22:23], v[16:17], v[24:25], v[22:23]
	global_store_dword v[26:27], v7, off
	v_add_u32_e32 v7, 0x8000, v22
	v_add_u32_e32 v22, 0x8000, v23
	v_lshl_add_u64 v[24:25], v[14:15], 0, s[38:39]
	v_perm_b32 v7, v22, v7, s25
	v_lshl_add_u64 v[22:23], v[20:21], 0, s[34:35]
	v_lshlrev_b64 v[24:25], 8, v[24:25]
	global_store_dword v[26:27], v7, off offset:32
	v_or_b32_e32 v26, v24, v3
	v_mov_b32_e32 v27, v25
	v_lshlrev_b64 v[22:23], 8, v[22:23]
	v_lshl_add_u64 v[28:29], s[82:83], 0, v[26:27]
	v_or_b32_e32 v30, v22, v5
	v_mov_b32_e32 v31, v23
	v_lshl_add_u64 v[32:33], s[82:83], 0, v[30:31]
	v_mov_b32_e32 v3, v158
	v_mov_b32_e32 v5, v159
	v_lshl_add_u64 v[24:25], v[12:13], 0, v[24:25]
	v_lshl_add_u64 v[22:23], v[12:13], 0, v[22:23]
	v_lshl_add_u64 v[26:27], s[4:5], 0, v[26:27]
	v_lshl_add_u64 v[28:29], s[4:5], 0, v[30:31]
	v_add_u32_e32 v3, 0x8000, v3
	v_add_u32_e32 v5, 0x8000, v5
	global_store_short_d16_hi v[24:25], v3, off
	global_store_short_d16_hi v[22:23], v5, off
	v_mov_b32_e32 v26, v162
	s_nop 0
	v_mov_b32_e32 v27, v163
	v_pk_add_f32 v[26:27], v[26:27], 0 neg_lo:[1,1] neg_hi:[1,1]
	s_nop 0
	v_add_u32_e32 v5, 0x8000, v26
	v_add_u32_e32 v3, 0x8000, v27
	global_store_short_d16_hi v[24:25], v5, off offset:2
	global_store_short_d16_hi v[22:23], v3, off offset:2
	v_lshl_add_u64 v[22:23], v[8:9], 0, s[14:15]
	v_lshlrev_b64 v[22:23], 2, v[22:23]
	v_lshl_add_u64 v[24:25], s[78:79], 0, v[22:23]
	v_lshl_add_u64 v[22:23], s[80:81], 0, v[22:23]
	v_mov_b32_e32 v22, v164
	v_mov_b32_e32 v23, v165
	s_mov_b32 s37, s15
	v_mov_b32_e32 v24, v168
	v_mov_b32_e32 v25, v169
	s_add_i32 s38, s14, 2
; DEVINL u16 f2bf(float f) { return (u16)((__float_as_uint(f) + 0x8000u) >> 16); }
; DEVINL void s5_param(const Params& p, int idx) {
;     ...
;   for (int j = 0; j < 16; ++j) {
;     float br = p.b_re[(size_t)idx * 16 + j], bi = p.b_im[(size_t)idx * 16 + j];
;     bbt[((size_t)g * 128 + 2 * n) * 16 + j] = f2bf(fr * br - fi * bi);
;     bbt[((size_t)g * 128 + 2 * n + 1) * 16 + j] = f2bf(fr * bi + fi * br);
;     ct[((size_t)g * 16 + j) * 128 + 2 * n] = f2bf(p.c_re[((size_t)g * 16 + j) * 64 + n]);
;     ct[((size_t)g * 16 + j) * 128 + 2 * n + 1] = f2bf(-p.c_im[((size_t)g * 16 + j) * 64 + n]);
;   }
	s_mov_b32 s39, s15
	s_add_i32 s34, s36, 2
	s_mov_b32 s35, s15
	s_add_i32 s0, s0, -4
	v_pk_mul_f32 v[26:27], v[16:17], v[22:23]
	v_pk_mul_f32 v[22:23], v[18:19], v[22:23]
	v_pk_fma_f32 v[26:27], v[18:19], v[24:25], v[26:27] neg_lo:[0,0,1] neg_hi:[0,0,1]
	v_pk_fma_f32 v[22:23], v[16:17], v[24:25], v[22:23]
	v_add_u32_e32 v3, 0x8000, v26
	v_add_u32_e32 v5, 0x8000, v27
	v_perm_b32 v3, v5, v3, s25
	v_lshl_add_u64 v[26:27], s[14:15], 1, v[10:11]
	global_store_dword v[26:27], v3, off
	v_add_u32_e32 v3, 0x8000, v22
	v_add_u32_e32 v5, 0x8000, v23
	v_perm_b32 v3, v5, v3, s25
	v_lshl_add_u64 v[24:25], v[14:15], 0, s[14:15]
	global_store_dword v[26:27], v3, off offset:32
	v_lshl_add_u64 v[22:23], v[20:21], 0, s[36:37]
	v_lshlrev_b64 v[24:25], 8, v[24:25]
	v_lshlrev_b32_e32 v3, 2, v4
	v_or_b32_e32 v26, v24, v3
	v_mov_b32_e32 v27, v25
	v_lshlrev_b64 v[22:23], 8, v[22:23]
	v_lshlrev_b32_e32 v5, 2, v6
	v_lshl_add_u64 v[28:29], s[82:83], 0, v[26:27]
	v_or_b32_e32 v30, v22, v5
	v_mov_b32_e32 v31, v23
	v_lshl_add_u64 v[32:33], s[82:83], 0, v[30:31]
	v_mov_b32_e32 v7, v172
	s_nop 0
	v_mov_b32_e32 v28, v173
	v_lshl_add_u64 v[24:25], v[12:13], 0, v[24:25]
	v_lshl_add_u64 v[22:23], v[12:13], 0, v[22:23]
	v_lshl_add_u64 v[26:27], s[4:5], 0, v[26:27]
	s_add_i32 s14, s14, 4
	s_add_i32 s36, s36, 4
	s_cmp_lg_u32 s0, 0
	v_add_u32_e32 v7, 0x8000, v7
	v_add_u32_e32 v28, 0x8000, v28
	global_store_short_d16_hi v[24:25], v7, off
	global_store_short_d16_hi v[22:23], v28, off
	v_lshl_add_u64 v[28:29], s[4:5], 0, v[30:31]
	v_mov_b32_e32 v26, v176
	s_nop 0
	v_mov_b32_e32 v27, v177
	v_pk_add_f32 v[26:27], v[26:27], 0 neg_lo:[1,1] neg_hi:[1,1]
	s_nop 0
	v_add_u32_e32 v26, 0x8000, v26
	v_add_u32_e32 v7, 0x8000, v27
	global_store_short_d16_hi v[24:25], v26, off offset:2
	global_store_short_d16_hi v[22:23], v7, off offset:2
	v_lshl_add_u64 v[22:23], v[8:9], 0, s[38:39]
	v_lshlrev_b64 v[22:23], 2, v[22:23]
	v_lshl_add_u64 v[24:25], s[78:79], 0, v[22:23]
	v_lshl_add_u64 v[22:23], s[80:81], 0, v[22:23]
	v_mov_b32_e32 v22, v166
	v_mov_b32_e32 v23, v167
	v_pk_mul_f32 v[26:27], v[16:17], v[22:23]
	v_mov_b32_e32 v24, v170
	v_mov_b32_e32 v25, v171
	v_pk_mul_f32 v[22:23], v[18:19], v[22:23]
	v_pk_fma_f32 v[26:27], v[18:19], v[24:25], v[26:27] neg_lo:[0,0,1] neg_hi:[0,0,1]
	s_nop 0
	v_add_u32_e32 v7, 0x8000, v26
	v_add_u32_e32 v26, 0x8000, v27
	v_perm_b32 v7, v26, v7, s25
	v_lshl_add_u64 v[26:27], s[38:39], 1, v[10:11]
	v_pk_fma_f32 v[22:23], v[16:17], v[24:25], v[22:23]
	global_store_dword v[26:27], v7, off
	v_add_u32_e32 v7, 0x8000, v22
	v_add_u32_e32 v22, 0x8000, v23
	v_lshl_add_u64 v[24:25], v[14:15], 0, s[38:39]
	v_perm_b32 v7, v22, v7, s25
	v_lshl_add_u64 v[22:23], v[20:21], 0, s[34:35]
	v_lshlrev_b64 v[24:25], 8, v[24:25]
	global_store_dword v[26:27], v7, off offset:32
	v_or_b32_e32 v26, v24, v3
	v_mov_b32_e32 v27, v25
	v_lshlrev_b64 v[22:23], 8, v[22:23]
	v_lshl_add_u64 v[28:29], s[82:83], 0, v[26:27]
	v_or_b32_e32 v30, v22, v5
	v_mov_b32_e32 v31, v23
	v_lshl_add_u64 v[32:33], s[82:83], 0, v[30:31]
	v_mov_b32_e32 v3, v174
	v_mov_b32_e32 v5, v175
	v_lshl_add_u64 v[24:25], v[12:13], 0, v[24:25]
	v_lshl_add_u64 v[22:23], v[12:13], 0, v[22:23]
	v_lshl_add_u64 v[26:27], s[4:5], 0, v[26:27]
	v_lshl_add_u64 v[28:29], s[4:5], 0, v[30:31]
	v_add_u32_e32 v3, 0x8000, v3
	v_add_u32_e32 v5, 0x8000, v5
	global_store_short_d16_hi v[24:25], v3, off
	global_store_short_d16_hi v[22:23], v5, off
	v_mov_b32_e32 v26, v178
	s_nop 0
	v_mov_b32_e32 v27, v179
	v_pk_add_f32 v[26:27], v[26:27], 0 neg_lo:[1,1] neg_hi:[1,1]
	s_nop 0
	v_add_u32_e32 v5, 0x8000, v26
	v_add_u32_e32 v3, 0x8000, v27
	global_store_short_d16_hi v[24:25], v5, off offset:2
	global_store_short_d16_hi v[22:23], v3, off offset:2
